# GEMM K-loop second half: LDS read base addresses from literals instead of SALU temporaries; otherwise v148
# baseline (speedup 1.0000x reference)
.LBB0_223:
	s_add_i32 s10, s8, 2
	s_add_u32 s11, s6, 0x80
	s_addc_u32 s9, s7, 0
	s_add_i32 s17, 0, 0x10000
	s_cmp_eq_u32 s45, s8
	s_cselect_b32 s9, s73, s9
	s_cselect_b32 s8, s72, s11
	s_cselect_b32 s19, s5, s16
	s_cselect_b32 s18, s4, s15
	s_add_i32 s11, 0, 0x14000
	v_add_u32_e32 v156, s17, v191
	v_add_u32_e32 v172, s11, v191
	ds_read_b128 v[144:147], v156
	ds_read_b128 v[148:151], v156 offset:1024
	ds_read_b128 v[152:155], v156 offset:2048
	ds_read_b128 v[156:159], v156 offset:3072
	ds_read_b128 v[160:163], v172
	ds_read_b128 v[164:167], v172 offset:1024
	ds_read_b128 v[168:171], v172 offset:2048
	ds_read_b128 v[172:175], v172 offset:3072
	v_lshl_add_u64 v[188:189], s[6:7], 0, v[140:141]
	s_add_i32 m0, s75, 0xc000
	ds_read_b128 v[176:179], v193
	ds_read_b128 v[180:183], v193 offset:1024
	ds_read_b128 v[184:187], v193 offset:2048
	ds_read_b128 v[194:197], v193 offset:3072
	ds_read_b128 v[198:201], v193 offset:4096
	ds_read_b128 v[204:207], v193 offset:5120
	ds_read_b128 v[214:217], v193 offset:6144
	ds_read_b128 v[218:221], v193 offset:7168
	global_load_lds_dwordx4 v[188:189], off
	v_lshl_add_u64 v[188:189], s[6:7], 0, v[138:139]
	s_add_i32 m0, s75, 0xe000
	s_nop 0
	global_load_lds_dwordx4 v[188:189], off
	s_waitcnt vmcnt(8)
	s_waitcnt lgkmcnt(0)
	s_barrier
	s_setprio 1
	s_waitcnt lgkmcnt(0)
	v_mfma_f32_16x16x32_bf16 v[126:129], v[144:147], v[176:179], v[126:129]
	v_mfma_f32_16x16x32_bf16 v[122:125], v[152:155], v[176:179], v[122:125]
	v_mfma_f32_16x16x32_bf16 v[110:113], v[144:147], v[184:187], v[110:113]
	v_mfma_f32_16x16x32_bf16 v[106:109], v[152:155], v[184:187], v[106:109]
	v_mfma_f32_16x16x32_bf16 v[94:97], v[144:147], v[198:201], v[94:97]
	v_mfma_f32_16x16x32_bf16 v[90:93], v[152:155], v[198:201], v[90:93]
	v_mfma_f32_16x16x32_bf16 v[78:81], v[144:147], v[214:217], v[78:81]
	v_mfma_f32_16x16x32_bf16 v[74:77], v[152:155], v[214:217], v[74:77]
	v_mfma_f32_16x16x32_bf16 v[126:129], v[148:151], v[180:183], v[126:129]
	v_mfma_f32_16x16x32_bf16 v[122:125], v[156:159], v[180:183], v[122:125]
	v_mfma_f32_16x16x32_bf16 v[110:113], v[148:151], v[194:197], v[110:113]
	v_mfma_f32_16x16x32_bf16 v[106:109], v[156:159], v[194:197], v[106:109]
	v_mfma_f32_16x16x32_bf16 v[94:97], v[148:151], v[204:207], v[94:97]
	v_mfma_f32_16x16x32_bf16 v[90:93], v[156:159], v[204:207], v[90:93]
	v_mfma_f32_16x16x32_bf16 v[78:81], v[148:151], v[218:221], v[78:81]
	v_mfma_f32_16x16x32_bf16 v[74:77], v[156:159], v[218:221], v[74:77]
	s_setprio 0
	s_setprio 1
	v_mfma_f32_16x16x32_bf16 v[118:121], v[160:163], v[176:179], v[118:121]
	v_mfma_f32_16x16x32_bf16 v[114:117], v[168:171], v[176:179], v[114:117]
	v_mfma_f32_16x16x32_bf16 v[102:105], v[160:163], v[184:187], v[102:105]
	v_mfma_f32_16x16x32_bf16 v[98:101], v[168:171], v[184:187], v[98:101]
	v_mfma_f32_16x16x32_bf16 v[86:89], v[160:163], v[198:201], v[86:89]
	v_mfma_f32_16x16x32_bf16 v[82:85], v[168:171], v[198:201], v[82:85]
	v_mfma_f32_16x16x32_bf16 v[70:73], v[160:163], v[214:217], v[70:73]
	v_mfma_f32_16x16x32_bf16 v[66:69], v[168:171], v[214:217], v[66:69]
	v_mfma_f32_16x16x32_bf16 v[118:121], v[164:167], v[180:183], v[118:121]
	v_mfma_f32_16x16x32_bf16 v[114:117], v[172:175], v[180:183], v[114:117]
	v_mfma_f32_16x16x32_bf16 v[102:105], v[164:167], v[194:197], v[102:105]
	v_mfma_f32_16x16x32_bf16 v[98:101], v[172:175], v[194:197], v[98:101]
	v_mfma_f32_16x16x32_bf16 v[86:89], v[164:167], v[204:207], v[86:89]
	v_mfma_f32_16x16x32_bf16 v[82:85], v[172:175], v[204:207], v[82:85]
	v_mfma_f32_16x16x32_bf16 v[70:73], v[164:167], v[218:221], v[70:73]
	v_mfma_f32_16x16x32_bf16 v[66:69], v[172:175], v[218:221], v[66:69]
	s_setprio 0
	s_barrier
	s_add_i32 s17, s17, s74
	v_lshl_add_u64 v[188:189], s[18:19], 0, v[132:133]
	s_mov_b32 m0, s17
	ds_read_b128 v[176:179], v193 offset:16384
	ds_read_b128 v[180:183], v193 offset:17408
	ds_read_b128 v[184:187], v193 offset:18432
	ds_read_b128 v[194:197], v193 offset:19456
	ds_read_b128 v[198:201], v193 offset:20480
	ds_read_b128 v[204:207], v193 offset:21504
	ds_read_b128 v[214:217], v193 offset:22528
	ds_read_b128 v[218:221], v193 offset:23552
	global_load_lds_dwordx4 v[188:189], off
	s_add_i32 m0, s17, 0x2000
	v_lshl_add_u64 v[222:223], s[18:19], 0, v[136:137]
	s_add_u32 s18, s18, s56
	s_addc_u32 s19, s19, 0
	s_add_i32 s11, s11, s74
	global_load_lds_dwordx4 v[222:223], off
	v_lshl_add_u64 v[224:225], s[18:19], 0, v[132:133]
	s_mov_b32 m0, s11
	v_lshl_add_u64 v[226:227], s[18:19], 0, v[136:137]
	global_load_lds_dwordx4 v[224:225], off
	s_add_i32 m0, s11, 0x2000
	v_lshl_add_u64 v[228:229], s[8:9], 0, v[130:131]
	global_load_lds_dwordx4 v[226:227], off
	s_mov_b32 m0, s75
	v_lshl_add_u64 v[230:231], s[8:9], 0, v[134:135]
	global_load_lds_dwordx4 v[228:229], off
	s_mov_b32 m0, s60
	s_nop 0
	global_load_lds_dwordx4 v[230:231], off
	s_waitcnt vmcnt(8)
	s_waitcnt lgkmcnt(0)
	s_barrier
	s_setprio 1
	s_waitcnt lgkmcnt(0)
	v_mfma_f32_16x16x32_bf16 v[62:65], v[144:147], v[176:179], v[62:65]
	v_mfma_f32_16x16x32_bf16 v[58:61], v[152:155], v[176:179], v[58:61]
	v_mfma_f32_16x16x32_bf16 v[46:49], v[144:147], v[184:187], v[46:49]
	v_mfma_f32_16x16x32_bf16 v[42:45], v[152:155], v[184:187], v[42:45]
	v_mfma_f32_16x16x32_bf16 v[30:33], v[144:147], v[198:201], v[30:33]
	v_mfma_f32_16x16x32_bf16 v[26:29], v[152:155], v[198:201], v[26:29]
	v_mfma_f32_16x16x32_bf16 v[14:17], v[144:147], v[214:217], v[14:17]
	v_mfma_f32_16x16x32_bf16 v[10:13], v[152:155], v[214:217], v[10:13]
	v_mfma_f32_16x16x32_bf16 v[62:65], v[148:151], v[180:183], v[62:65]
	v_mfma_f32_16x16x32_bf16 v[58:61], v[156:159], v[180:183], v[58:61]
	v_mfma_f32_16x16x32_bf16 v[46:49], v[148:151], v[194:197], v[46:49]
	v_mfma_f32_16x16x32_bf16 v[42:45], v[156:159], v[194:197], v[42:45]
	v_mfma_f32_16x16x32_bf16 v[30:33], v[148:151], v[204:207], v[30:33]
	v_mfma_f32_16x16x32_bf16 v[26:29], v[156:159], v[204:207], v[26:29]
	v_mfma_f32_16x16x32_bf16 v[14:17], v[148:151], v[218:221], v[14:17]
	v_mfma_f32_16x16x32_bf16 v[10:13], v[156:159], v[218:221], v[10:13]
	s_setprio 0
	s_setprio 1
	v_mfma_f32_16x16x32_bf16 v[54:57], v[160:163], v[176:179], v[54:57]
	v_mfma_f32_16x16x32_bf16 v[50:53], v[168:171], v[176:179], v[50:53]
	v_mfma_f32_16x16x32_bf16 v[38:41], v[160:163], v[184:187], v[38:41]
	v_mfma_f32_16x16x32_bf16 v[34:37], v[168:171], v[184:187], v[34:37]
	v_mfma_f32_16x16x32_bf16 v[22:25], v[160:163], v[198:201], v[22:25]
	v_mfma_f32_16x16x32_bf16 v[18:21], v[168:171], v[198:201], v[18:21]
	v_mfma_f32_16x16x32_bf16 v[6:9], v[160:163], v[214:217], v[6:9]
	v_mfma_f32_16x16x32_bf16 v[2:5], v[168:171], v[214:217], v[2:5]
	v_mfma_f32_16x16x32_bf16 v[54:57], v[164:167], v[180:183], v[54:57]
	v_mfma_f32_16x16x32_bf16 v[50:53], v[172:175], v[180:183], v[50:53]
	v_mfma_f32_16x16x32_bf16 v[38:41], v[164:167], v[194:197], v[38:41]
	v_mfma_f32_16x16x32_bf16 v[34:37], v[172:175], v[194:197], v[34:37]
	v_mfma_f32_16x16x32_bf16 v[22:25], v[164:167], v[204:207], v[22:25]
	v_mfma_f32_16x16x32_bf16 v[18:21], v[172:175], v[204:207], v[18:21]
	v_mfma_f32_16x16x32_bf16 v[6:9], v[164:167], v[218:221], v[6:9]
	v_mfma_f32_16x16x32_bf16 v[2:5], v[172:175], v[218:221], v[2:5]
	s_setprio 0
	s_barrier
	s_add_i32 s11, 0, 0x18000
	s_add_i32 s17, 0, 0x1c000
	v_add_u32_e32 v156, 0x18000, v191
	v_add_u32_e32 v172, 0x1c000, v191
	ds_read_b128 v[144:147], v156
	ds_read_b128 v[148:151], v156 offset:1024
	ds_read_b128 v[152:155], v156 offset:2048
	ds_read_b128 v[156:159], v156 offset:3072
	ds_read_b128 v[160:163], v172
	ds_read_b128 v[164:167], v172 offset:1024
	ds_read_b128 v[168:171], v172 offset:2048
	ds_read_b128 v[172:175], v172 offset:3072
	s_add_u32 s8, s8, s56
	s_addc_u32 s9, s9, 0
	s_mov_b32 m0, s61
	v_lshl_add_u64 v[232:233], s[8:9], 0, v[130:131]
	ds_read_b128 v[176:179], v193 offset:32768
	ds_read_b128 v[180:183], v193 offset:33792
	ds_read_b128 v[184:187], v193 offset:34816
	ds_read_b128 v[194:197], v193 offset:35840
	ds_read_b128 v[198:201], v193 offset:36864
	ds_read_b128 v[204:207], v193 offset:37888
	ds_read_b128 v[214:217], v193 offset:38912
	ds_read_b128 v[218:221], v193 offset:39936
	global_load_lds_dwordx4 v[232:233], off
	v_lshl_add_u64 v[232:233], s[8:9], 0, v[134:135]
	s_mov_b32 m0, s46
	s_nop 0
	global_load_lds_dwordx4 v[232:233], off
	s_waitcnt vmcnt(8)
	s_waitcnt lgkmcnt(0)
	s_barrier
	s_setprio 1
	s_waitcnt lgkmcnt(0)
	v_mfma_f32_16x16x32_bf16 v[126:129], v[144:147], v[176:179], v[126:129]
	v_mfma_f32_16x16x32_bf16 v[122:125], v[152:155], v[176:179], v[122:125]
	v_mfma_f32_16x16x32_bf16 v[110:113], v[144:147], v[184:187], v[110:113]
	v_mfma_f32_16x16x32_bf16 v[106:109], v[152:155], v[184:187], v[106:109]
	v_mfma_f32_16x16x32_bf16 v[94:97], v[144:147], v[198:201], v[94:97]
	v_mfma_f32_16x16x32_bf16 v[90:93], v[152:155], v[198:201], v[90:93]
	v_mfma_f32_16x16x32_bf16 v[78:81], v[144:147], v[214:217], v[78:81]
	v_mfma_f32_16x16x32_bf16 v[74:77], v[152:155], v[214:217], v[74:77]
	v_mfma_f32_16x16x32_bf16 v[126:129], v[148:151], v[180:183], v[126:129]
	v_mfma_f32_16x16x32_bf16 v[122:125], v[156:159], v[180:183], v[122:125]
	v_mfma_f32_16x16x32_bf16 v[110:113], v[148:151], v[194:197], v[110:113]
	v_mfma_f32_16x16x32_bf16 v[106:109], v[156:159], v[194:197], v[106:109]
	v_mfma_f32_16x16x32_bf16 v[94:97], v[148:151], v[204:207], v[94:97]
	v_mfma_f32_16x16x32_bf16 v[90:93], v[156:159], v[204:207], v[90:93]
	v_mfma_f32_16x16x32_bf16 v[78:81], v[148:151], v[218:221], v[78:81]
	v_mfma_f32_16x16x32_bf16 v[74:77], v[156:159], v[218:221], v[74:77]
	s_setprio 0
	s_setprio 1
	v_mfma_f32_16x16x32_bf16 v[118:121], v[160:163], v[176:179], v[118:121]
	v_mfma_f32_16x16x32_bf16 v[114:117], v[168:171], v[176:179], v[114:117]
	v_mfma_f32_16x16x32_bf16 v[102:105], v[160:163], v[184:187], v[102:105]
	v_mfma_f32_16x16x32_bf16 v[98:101], v[168:171], v[184:187], v[98:101]
	v_mfma_f32_16x16x32_bf16 v[86:89], v[160:163], v[198:201], v[86:89]
	v_mfma_f32_16x16x32_bf16 v[82:85], v[168:171], v[198:201], v[82:85]
	v_mfma_f32_16x16x32_bf16 v[70:73], v[160:163], v[214:217], v[70:73]
	v_mfma_f32_16x16x32_bf16 v[66:69], v[168:171], v[214:217], v[66:69]
	v_mfma_f32_16x16x32_bf16 v[118:121], v[164:167], v[180:183], v[118:121]
	v_mfma_f32_16x16x32_bf16 v[114:117], v[172:175], v[180:183], v[114:117]
	v_mfma_f32_16x16x32_bf16 v[102:105], v[164:167], v[194:197], v[102:105]
	v_mfma_f32_16x16x32_bf16 v[98:101], v[172:175], v[194:197], v[98:101]
	v_mfma_f32_16x16x32_bf16 v[86:89], v[164:167], v[204:207], v[86:89]
	v_mfma_f32_16x16x32_bf16 v[82:85], v[172:175], v[204:207], v[82:85]
	v_mfma_f32_16x16x32_bf16 v[70:73], v[164:167], v[218:221], v[70:73]
	v_mfma_f32_16x16x32_bf16 v[66:69], v[172:175], v[218:221], v[66:69]
	s_setprio 0
	s_barrier
	s_add_i32 s8, s11, s74
	v_lshl_add_u64 v[188:189], v[188:189], 0, s[30:31]
	s_mov_b32 m0, s8
	ds_read_b128 v[176:179], v193 offset:49152
	ds_read_b128 v[180:183], v193 offset:50176
	ds_read_b128 v[184:187], v193 offset:51200
	ds_read_b128 v[194:197], v193 offset:52224
	ds_read_b128 v[198:201], v193 offset:53248
	ds_read_b128 v[204:207], v193 offset:54272
	ds_read_b128 v[214:217], v193 offset:55296
	ds_read_b128 v[218:221], v193 offset:56320
	global_load_lds_dwordx4 v[188:189], off
	v_lshl_add_u64 v[188:189], v[222:223], 0, s[30:31]
	s_add_i32 m0, s8, 0x2000
	s_add_i32 s8, s17, s74
	global_load_lds_dwordx4 v[188:189], off
	v_lshl_add_u64 v[188:189], v[224:225], 0, s[30:31]
	s_mov_b32 m0, s8
	s_nop 0
	global_load_lds_dwordx4 v[188:189], off
	v_lshl_add_u64 v[188:189], v[226:227], 0, s[30:31]
	s_add_i32 m0, s8, 0x2000
	s_nop 0
	global_load_lds_dwordx4 v[188:189], off
	v_lshl_add_u64 v[188:189], v[228:229], 0, s[30:31]
	s_mov_b32 m0, s63
	s_nop 0
	global_load_lds_dwordx4 v[188:189], off
	v_lshl_add_u64 v[188:189], v[230:231], 0, s[30:31]
	s_mov_b32 m0, s44
	s_nop 0
	global_load_lds_dwordx4 v[188:189], off
	s_waitcnt vmcnt(8)
	s_waitcnt lgkmcnt(0)
	s_barrier
	s_setprio 1
	s_waitcnt lgkmcnt(0)
	v_mfma_f32_16x16x32_bf16 v[62:65], v[144:147], v[176:179], v[62:65]
	v_mfma_f32_16x16x32_bf16 v[58:61], v[152:155], v[176:179], v[58:61]
	v_mfma_f32_16x16x32_bf16 v[46:49], v[144:147], v[184:187], v[46:49]
	v_mfma_f32_16x16x32_bf16 v[42:45], v[152:155], v[184:187], v[42:45]
	v_mfma_f32_16x16x32_bf16 v[30:33], v[144:147], v[198:201], v[30:33]
	v_mfma_f32_16x16x32_bf16 v[26:29], v[152:155], v[198:201], v[26:29]
	v_mfma_f32_16x16x32_bf16 v[14:17], v[144:147], v[214:217], v[14:17]
	v_mfma_f32_16x16x32_bf16 v[10:13], v[152:155], v[214:217], v[10:13]
	v_mfma_f32_16x16x32_bf16 v[62:65], v[148:151], v[180:183], v[62:65]
	v_mfma_f32_16x16x32_bf16 v[58:61], v[156:159], v[180:183], v[58:61]
	v_mfma_f32_16x16x32_bf16 v[46:49], v[148:151], v[194:197], v[46:49]
	v_mfma_f32_16x16x32_bf16 v[42:45], v[156:159], v[194:197], v[42:45]
	v_mfma_f32_16x16x32_bf16 v[30:33], v[148:151], v[204:207], v[30:33]
	v_mfma_f32_16x16x32_bf16 v[26:29], v[156:159], v[204:207], v[26:29]
	v_mfma_f32_16x16x32_bf16 v[14:17], v[148:151], v[218:221], v[14:17]
	v_mfma_f32_16x16x32_bf16 v[10:13], v[156:159], v[218:221], v[10:13]
	s_setprio 0
	s_setprio 1
	v_mfma_f32_16x16x32_bf16 v[54:57], v[160:163], v[176:179], v[54:57]
	v_mfma_f32_16x16x32_bf16 v[50:53], v[168:171], v[176:179], v[50:53]
	v_mfma_f32_16x16x32_bf16 v[38:41], v[160:163], v[184:187], v[38:41]
	v_mfma_f32_16x16x32_bf16 v[34:37], v[168:171], v[184:187], v[34:37]
	v_mfma_f32_16x16x32_bf16 v[22:25], v[160:163], v[198:201], v[22:25]
	v_mfma_f32_16x16x32_bf16 v[18:21], v[168:171], v[198:201], v[18:21]
	v_mfma_f32_16x16x32_bf16 v[6:9], v[160:163], v[214:217], v[6:9]
	v_mfma_f32_16x16x32_bf16 v[2:5], v[168:171], v[214:217], v[2:5]
	v_mfma_f32_16x16x32_bf16 v[54:57], v[164:167], v[180:183], v[54:57]
	v_mfma_f32_16x16x32_bf16 v[50:53], v[172:175], v[180:183], v[50:53]
	v_mfma_f32_16x16x32_bf16 v[38:41], v[164:167], v[194:197], v[38:41]
	v_mfma_f32_16x16x32_bf16 v[34:37], v[172:175], v[194:197], v[34:37]
	v_mfma_f32_16x16x32_bf16 v[22:25], v[164:167], v[204:207], v[22:25]
	v_mfma_f32_16x16x32_bf16 v[18:21], v[172:175], v[204:207], v[18:21]
	v_mfma_f32_16x16x32_bf16 v[6:9], v[164:167], v[218:221], v[6:9]
	v_mfma_f32_16x16x32_bf16 v[2:5], v[172:175], v[218:221], v[2:5]
	s_setprio 0
	s_barrier
	s_add_u32 s15, s15, 0x100
	s_addc_u32 s16, s16, 0
	s_add_u32 s6, s6, 0x100
	s_addc_u32 s7, s7, 0
	s_cmp_ge_u32 s10, s47
	s_mov_b32 s8, s10
	s_cbranch_scc0 .LBB0_223
	v_readlane_b32 s6, v243, 45
	v_readlane_b32 s7, v243, 46
	s_and_b64 vcc, exec, s[6:7]
	s_cbranch_vccz .LBB0_226
	s_barrier
